# v069 + the tile's four LDS-DMA pieces issued between the first four QK MFMAs instead of in front of the K reads
# speedup vs baseline: 1.0078x; 1.0078x over previous
; template <int N> __device__ __forceinline__ void wait_bar() { asm volatile("s_waitcnt vmcnt(%0) lgkmcnt(0)\n\ts_barrier" :: "n"(N) : "memory"); }
; #define AT_DMA(tr) do { const unsigned sb_ = (unsigned)__builtin_amdgcn_readfirstlane(dk + (((tr) & (NSTG - 1)) * STAGE)); const size_t ko_ = (size_t)(tr) * 26 * 4096, vo_ = (size_t)(tr) * 640 * 64; \
;         glds16(kg + ko_, sb_ + OFF_K0); if (!WIN) glds16(kg + ko_ + 4096, sb_ + OFF_K1); glds16(vg + vo_, sb_ + OFF_V); if (!WIN) glds16(vg + vo_ + 64 * 64, sb_ + OFF_V + 8192); } while (0)
; template <bool WIN> ...
;     ...
;         if (tr + 2 < NT) wait_bar<2 * NPW>(); else if (tr + 1 < NT) wait_bar<NPW>(); else wait_bar<0>();
;         if (tr + 3 < NT) AT_DMA(tr + 3);
;         const int k0 = (t_lo + tr) * 64;
;         const bool skip = WIN && (k0 > qw + 31 + 128 || k0 + 63 < qw - 128);
.LSPp_t0d:
	s_cmpk_gt_u32 s86, 124
	s_cbranch_scc0 .LSPp_scal
	s_cmpk_gt_u32 s86, 124
	s_cbranch_scc1 .LSPp_skipk
	s_add_i32 s98, s85, 0x8000
	s_and_b32 s98, s98, 0x18000
	s_add_i32 s98, s98, s20
	s_mov_b32 m0, s98
	v_lshl_add_u64 v[82:83], v[174:175], 0, s[40:41]
	global_load_lds_dwordx4 v[174:175], off
	s_add_i32 m0, s98, 0x2000
	s_nop 0
	global_load_lds_dwordx4 v[82:83], off

; #define ALAS __attribute__((address_space(3)))
; template <bool WIN> ...
;     ...
;             {
;                 bf16x8 ka[8];
; #pragma unroll
;                 for (int ds = 0; ds < 4; ++ds) { ka[2 * ds] = *(const ALAS bf16x8*)(sb + kx[ds]); ka[2 * ds + 1] = *(const ALAS bf16x8*)(sb + kx[ds] + 4096); }
;                 __builtin_amdgcn_sched_barrier(0);
;                 s0 = __builtin_amdgcn_mfma_f32_32x32x16_bf16(ka[0], qf(0), cvec, 0, 0, 0);
;                 s1 = __builtin_amdgcn_mfma_f32_32x32x16_bf16(ka[1], qf(0), cvec, 0, 0, 0);
; #pragma unroll
;                 for (int ds = 1; ds < 4; ++ds) {
;                     s0 = __builtin_amdgcn_mfma_f32_32x32x16_bf16(ka[2 * ds], qf(ds), s0, 0, 0, 0);
;                     s1 = __builtin_amdgcn_mfma_f32_32x32x16_bf16(ka[2 * ds + 1], qf(ds), s1, 0, 0, 0);
;                 }
;             }
.LSPp_qk:
	s_add_i32 s87, s85, 0xffff0000
	s_and_b32 s87, s87, 0x18000
	s_add_i32 s99, s85, 0xfffe8000
	s_and_b32 s99, s99, 0x18000
	v_add3_u32 v203, s87, v178, v162
	ds_read_b128 v[130:133], v203
	ds_read_b128 v[134:137], v203 offset:4096
	v_add3_u32 v203, s87, v180, v162
	ds_read_b128 v[138:141], v203
	ds_read_b128 v[142:145], v203 offset:4096
	v_add3_u32 v203, s87, v182, v162
	ds_read_b128 v[146:149], v203
	ds_read_b128 v[150:153], v203 offset:4096
	v_add3_u32 v203, s87, v184, v162
	ds_read_b128 v[158:161], v203
	ds_read_b128 v[204:207], v203 offset:4096
	s_add_i32 s98, s85, 0x8000
	s_and_b32 s98, s98, 0x18000
	s_add_i32 s98, s98, s20
	s_and_b32 s101, s85, 0x18000
	s_add_i32 s101, s101, s20
	v_lshl_add_u64 v[208:209], v[174:175], 0, s[40:41]
	v_lshl_add_u64 v[210:211], v[172:173], 0, s[40:41]
	s_cmpk_gt_u32 s86, 124
	s_cbranch_scc1 .LSPp_qkplain
	s_mov_b32 m0, s98
	s_waitcnt lgkmcnt(0)
	v_mfma_f32_32x32x16_bf16 v[98:113], v[130:133], v[126:129], v[66:81]
	global_load_lds_dwordx4 v[174:175], off
	s_add_i32 m0, s98, 0x2000
	v_mfma_f32_32x32x16_bf16 v[82:97], v[134:137], v[126:129], v[66:81]
	global_load_lds_dwordx4 v[208:209], off
	s_add_i32 m0, s101, 0x4000
	v_mfma_f32_32x32x16_bf16 v[98:113], v[138:141], v[122:125], v[98:113]
	global_load_lds_dwordx4 v[172:173], off
	s_add_i32 m0, s101, 0x6000
	v_mfma_f32_32x32x16_bf16 v[82:97], v[142:145], v[122:125], v[82:97]
	global_load_lds_dwordx4 v[210:211], off
	v_mfma_f32_32x32x16_bf16 v[98:113], v[146:149], v[118:121], v[98:113]
	v_mfma_f32_32x32x16_bf16 v[82:97], v[150:153], v[118:121], v[82:97]
	v_mfma_f32_32x32x16_bf16 v[98:113], v[158:161], v[114:117], v[98:113]
	v_mfma_f32_32x32x16_bf16 v[82:97], v[204:207], v[114:117], v[82:97]
	s_branch .LSPp_vrd
.LSPp_qkplain:
	s_waitcnt lgkmcnt(0)
	v_mfma_f32_32x32x16_bf16 v[98:113], v[130:133], v[126:129], v[66:81]
	v_mfma_f32_32x32x16_bf16 v[82:97], v[134:137], v[126:129], v[66:81]
	v_mfma_f32_32x32x16_bf16 v[98:113], v[138:141], v[122:125], v[98:113]
	v_mfma_f32_32x32x16_bf16 v[82:97], v[142:145], v[122:125], v[82:97]
	v_mfma_f32_32x32x16_bf16 v[98:113], v[146:149], v[118:121], v[98:113]
	v_mfma_f32_32x32x16_bf16 v[82:97], v[150:153], v[118:121], v[82:97]
	v_mfma_f32_32x32x16_bf16 v[98:113], v[158:161], v[114:117], v[98:113]
	v_mfma_f32_32x32x16_bf16 v[82:97], v[204:207], v[114:117], v[82:97]
.LSPp_vrd:
	v_add3_u32 v236, s99, v179, v187
	ds_read_b128 v[146:149], v236 offset:16384
	ds_read_b128 v[150:153], v236 offset:20480
	ds_read_b128 v[154:157], v236 offset:24576
	ds_read_b128 v[158:161], v236 offset:28672
	v_add3_u32 v237, s99, v181, v187
	ds_read_b128 v[130:133], v237 offset:16384
	ds_read_b128 v[134:137], v237 offset:20480
	ds_read_b128 v[138:141], v237 offset:24576
	ds_read_b128 v[142:145], v237 offset:28672
	s_nop 1
	s_andn2_b64 vcc, exec, s[64:65]
	s_cbranch_vccnz .LSPp_pv
	v_add_u32_e32 v203, s84, v171
	v_add_u32_e32 v204, 0x23b80, v203
	v_add_u32_e32 v206, 0x23c00, v203
	v_add_u32_e32 v210, 0x23c08, v203
	v_add_u32_e32 v208, 0x23b88, v203
	v_add_u32_e32 v218, 0x23c10, v203
	v_add_u32_e32 v212, 0x23b90, v203
	v_add_u32_e32 v216, 0x23c18, v203
	v_add_u32_e32 v214, 0x23b98, v203
	ds_read2_b32 v[204:205], v204 offset1:1
	ds_read2_b32 v[206:207], v206 offset1:1
	ds_read2_b32 v[208:209], v208 offset1:1
	ds_read2_b32 v[210:211], v210 offset1:1
	ds_read2_b32 v[212:213], v212 offset1:1
	ds_read2_b32 v[214:215], v214 offset1:1
	ds_read2_b32 v[216:217], v216 offset1:1
	ds_read2_b32 v[218:219], v218 offset1:1
	v_add_u32_e32 v220, 0x23bc0, v203
	v_add_u32_e32 v222, 0x23c40, v203
	v_add_u32_e32 v226, 0x23c48, v203
	v_add_u32_e32 v224, 0x23bc8, v203
	v_add_u32_e32 v228, 0x23bd0, v203
	v_add_u32_e32 v234, 0x23c58, v203
	ds_read2_b32 v[220:221], v220 offset1:1
	ds_read2_b32 v[222:223], v222 offset1:1
	ds_read2_b32 v[224:225], v224 offset1:1
	ds_read2_b32 v[226:227], v226 offset1:1
	v_add_u32_e32 v231, 0x23c50, v203
	v_add_u32_e32 v203, 0x23bd8, v203
	ds_read2_b32 v[228:229], v228 offset1:1
	ds_read2_b32 v[232:233], v203 offset1:1
	ds_read2_b32 v[234:235], v234 offset1:1
	ds_read2_b32 v[236:237], v231 offset1:1
	s_waitcnt lgkmcnt(10)
	v_pk_add_f32 v[104:105], v[104:105], v[214:215]
	v_pk_add_f32 v[102:103], v[102:103], v[212:213]
	v_pk_add_f32 v[100:101], v[100:101], v[208:209]
	s_waitcnt lgkmcnt(2)
	v_pk_add_f32 v[112:113], v[112:113], v[232:233]
	v_pk_add_f32 v[110:111], v[110:111], v[228:229]
	v_pk_add_f32 v[108:109], v[108:109], v[224:225]
	v_pk_add_f32 v[106:107], v[106:107], v[220:221]
	v_pk_add_f32 v[98:99], v[98:99], v[204:205]
	v_pk_add_f32 v[88:89], v[88:89], v[216:217]
	v_pk_add_f32 v[86:87], v[86:87], v[218:219]
	v_pk_add_f32 v[84:85], v[84:85], v[210:211]
	s_waitcnt lgkmcnt(1)
	v_pk_add_f32 v[96:97], v[96:97], v[234:235]
	s_waitcnt lgkmcnt(0)
	v_pk_add_f32 v[94:95], v[94:95], v[236:237]
	v_pk_add_f32 v[92:93], v[92:93], v[226:227]
	v_pk_add_f32 v[90:91], v[90:91], v[222:223]
	v_pk_add_f32 v[82:83], v[82:83], v[206:207]

; template <int N> __device__ __forceinline__ void wait_bar() { asm volatile("s_waitcnt vmcnt(%0) lgkmcnt(0)\n\ts_barrier" :: "n"(N) : "memory"); }
; #define AT_DMA(tr) do { const unsigned sb_ = (unsigned)__builtin_amdgcn_readfirstlane(dk + (((tr) & (NSTG - 1)) * STAGE)); const size_t ko_ = (size_t)(tr) * 26 * 4096, vo_ = (size_t)(tr) * 640 * 64; \
;         glds16(kg + ko_, sb_ + OFF_K0); if (!WIN) glds16(kg + ko_ + 4096, sb_ + OFF_K1); glds16(vg + vo_, sb_ + OFF_V); if (!WIN) glds16(vg + vo_ + 64 * 64, sb_ + OFF_V + 8192); } while (0)
; template <bool WIN> ...
;     ...
;         if (tr + 2 < NT) wait_bar<2 * NPW>(); else if (tr + 1 < NT) wait_bar<NPW>(); else wait_bar<0>();
;         if (tr + 3 < NT) AT_DMA(tr + 3);
.LSPs_t0d:
	s_cmpk_gt_u32 s79, 28
	s_cbranch_scc0 .LSPs_scal
	s_cmpk_gt_u32 s79, 28
	s_cbranch_scc1 .LSPs_skipk
	s_add_i32 s98, s78, 0x8000
	s_and_b32 s98, s98, 0x18000
	s_add_i32 s98, s98, s29
	s_mov_b32 m0, s98
	v_lshl_add_u64 v[82:83], v[174:175], 0, s[40:41]
	global_load_lds_dwordx4 v[174:175], off
	s_add_i32 m0, s98, 0x2000
	s_nop 0
	global_load_lds_dwordx4 v[82:83], off

; #define ALAS __attribute__((address_space(3)))
; template <bool WIN> ...
;     ...
;             {
;                 bf16x8 ka[8];
; #pragma unroll
;                 for (int ds = 0; ds < 4; ++ds) { ka[2 * ds] = *(const ALAS bf16x8*)(sb + kx[ds]); ka[2 * ds + 1] = *(const ALAS bf16x8*)(sb + kx[ds] + 4096); }
;                 __builtin_amdgcn_sched_barrier(0);
;                 s0 = __builtin_amdgcn_mfma_f32_32x32x16_bf16(ka[0], qf(0), cvec, 0, 0, 0);
;                 s1 = __builtin_amdgcn_mfma_f32_32x32x16_bf16(ka[1], qf(0), cvec, 0, 0, 0);
; #pragma unroll
;                 for (int ds = 1; ds < 4; ++ds) {
;                     s0 = __builtin_amdgcn_mfma_f32_32x32x16_bf16(ka[2 * ds], qf(ds), s0, 0, 0, 0);
;                     s1 = __builtin_amdgcn_mfma_f32_32x32x16_bf16(ka[2 * ds + 1], qf(ds), s1, 0, 0, 0);
;                 }
;             }
.LSPs_qk:
	s_add_i32 s80, s78, 0xffff0000
	s_and_b32 s80, s80, 0x18000
	s_add_i32 s99, s78, 0xfffe8000
	s_and_b32 s99, s99, 0x18000
	v_add3_u32 v203, s80, v178, v162
	ds_read_b128 v[130:133], v203
	ds_read_b128 v[134:137], v203 offset:4096
	v_add3_u32 v203, s80, v180, v162
	ds_read_b128 v[138:141], v203
	ds_read_b128 v[142:145], v203 offset:4096
	v_add3_u32 v203, s80, v182, v162
	ds_read_b128 v[146:149], v203
	ds_read_b128 v[150:153], v203 offset:4096
	v_add3_u32 v203, s80, v184, v162
	ds_read_b128 v[158:161], v203
	ds_read_b128 v[204:207], v203 offset:4096
	s_add_i32 s98, s78, 0x8000
	s_and_b32 s98, s98, 0x18000
	s_add_i32 s98, s98, s29
	s_and_b32 s101, s78, 0x18000
	s_add_i32 s101, s101, s29
	v_lshl_add_u64 v[208:209], v[174:175], 0, s[40:41]
	v_lshl_add_u64 v[210:211], v[172:173], 0, s[40:41]
	s_cmpk_gt_u32 s79, 28
	s_cbranch_scc1 .LSPs_qkplain
	s_mov_b32 m0, s98
	s_waitcnt lgkmcnt(0)
	v_mfma_f32_32x32x16_bf16 v[98:113], v[130:133], v[126:129], v[66:81]
	global_load_lds_dwordx4 v[174:175], off
	s_add_i32 m0, s98, 0x2000
	v_mfma_f32_32x32x16_bf16 v[82:97], v[134:137], v[126:129], v[66:81]
	global_load_lds_dwordx4 v[208:209], off
	s_add_i32 m0, s101, 0x4000
	v_mfma_f32_32x32x16_bf16 v[98:113], v[138:141], v[122:125], v[98:113]
	global_load_lds_dwordx4 v[172:173], off
	s_add_i32 m0, s101, 0x6000
	v_mfma_f32_32x32x16_bf16 v[82:97], v[142:145], v[122:125], v[82:97]
	global_load_lds_dwordx4 v[210:211], off
	v_mfma_f32_32x32x16_bf16 v[98:113], v[146:149], v[118:121], v[98:113]
	v_mfma_f32_32x32x16_bf16 v[82:97], v[150:153], v[118:121], v[82:97]
	v_mfma_f32_32x32x16_bf16 v[98:113], v[158:161], v[114:117], v[98:113]
	v_mfma_f32_32x32x16_bf16 v[82:97], v[204:207], v[114:117], v[82:97]
	s_branch .LSPs_vrd

; #define ALAS __attribute__((address_space(3)))
; template <bool WIN> ...
;     ...
;             bf16x8 va[2 * NDB], vc[2 * NDB];
; #pragma unroll
;             for (int kk = 0; kk < 2; ++kk)
; #pragma unroll
;                 for (int db = 0; db < NDB; ++db) va[kk * NDB + db] = *(const ALAS bf16x8*)(sb + vx[kk] + db * 4096);
;             __builtin_amdgcn_sched_barrier(0);
;             if (near) {
;                 const ALAS float* lb = lut + (k0 + 8 * hi - qabs + LUTC);
; #pragma unroll
;                 for (int r = 0; r < 16; ++r) { s0[r] += lb[16 * (r >> 3) + (r & 7)]; s1[r] += lb[32 + 16 * (r >> 3) + (r & 7)];
;                     if ((r & 7) == 7) __builtin_amdgcn_sched_barrier(0); }
;             }
.LSPs_vrd:
	v_add3_u32 v236, s99, v179, v187
	ds_read_b128 v[146:149], v236 offset:16384
	ds_read_b128 v[150:153], v236 offset:20480
	ds_read_b128 v[154:157], v236 offset:24576
	ds_read_b128 v[158:161], v236 offset:28672
	v_add3_u32 v237, s99, v181, v187
	ds_read_b128 v[130:133], v237 offset:16384
	ds_read_b128 v[134:137], v237 offset:20480
	ds_read_b128 v[138:141], v237 offset:24576
	ds_read_b128 v[142:145], v237 offset:28672
	s_nop 1
	s_andn2_b64 vcc, exec, s[64:65]
	s_cbranch_vccnz .LSPs_pv
	v_add_u32_e32 v203, s77, v171
	v_add_u32_e32 v204, 0x23b80, v203
	v_add_u32_e32 v206, 0x23c00, v203
	v_add_u32_e32 v210, 0x23c08, v203
	v_add_u32_e32 v208, 0x23b88, v203
	v_add_u32_e32 v218, 0x23c10, v203
	v_add_u32_e32 v212, 0x23b90, v203
	v_add_u32_e32 v216, 0x23c18, v203
	v_add_u32_e32 v214, 0x23b98, v203
	ds_read2_b32 v[204:205], v204 offset1:1
	ds_read2_b32 v[206:207], v206 offset1:1
	ds_read2_b32 v[208:209], v208 offset1:1
	ds_read2_b32 v[210:211], v210 offset1:1
	ds_read2_b32 v[212:213], v212 offset1:1
	ds_read2_b32 v[214:215], v214 offset1:1
	ds_read2_b32 v[216:217], v216 offset1:1
	ds_read2_b32 v[218:219], v218 offset1:1
	v_add_u32_e32 v220, 0x23bc0, v203
	v_add_u32_e32 v222, 0x23c40, v203
	v_add_u32_e32 v226, 0x23c48, v203
	v_add_u32_e32 v224, 0x23bc8, v203
	v_add_u32_e32 v228, 0x23bd0, v203
	v_add_u32_e32 v234, 0x23c58, v203
	ds_read2_b32 v[220:221], v220 offset1:1
	ds_read2_b32 v[222:223], v222 offset1:1
	ds_read2_b32 v[224:225], v224 offset1:1
	ds_read2_b32 v[226:227], v226 offset1:1
	v_add_u32_e32 v231, 0x23c50, v203
	v_add_u32_e32 v203, 0x23bd8, v203
	ds_read2_b32 v[228:229], v228 offset1:1
	ds_read2_b32 v[232:233], v203 offset1:1
	ds_read2_b32 v[234:235], v234 offset1:1
	ds_read2_b32 v[236:237], v231 offset1:1
	s_waitcnt lgkmcnt(10)
	v_pk_add_f32 v[104:105], v[104:105], v[214:215]
	v_pk_add_f32 v[102:103], v[102:103], v[212:213]
	v_pk_add_f32 v[100:101], v[100:101], v[208:209]
	s_waitcnt lgkmcnt(2)
	v_pk_add_f32 v[112:113], v[112:113], v[232:233]
	v_pk_add_f32 v[110:111], v[110:111], v[228:229]
	v_pk_add_f32 v[108:109], v[108:109], v[224:225]
	v_pk_add_f32 v[106:107], v[106:107], v[220:221]
	v_pk_add_f32 v[98:99], v[98:99], v[204:205]
	v_pk_add_f32 v[88:89], v[88:89], v[216:217]
	v_pk_add_f32 v[86:87], v[86:87], v[218:219]
	v_pk_add_f32 v[84:85], v[84:85], v[210:211]
	s_waitcnt lgkmcnt(1)
	v_pk_add_f32 v[96:97], v[96:97], v[234:235]
	s_waitcnt lgkmcnt(0)
	v_pk_add_f32 v[94:95], v[94:95], v[236:237]
	v_pk_add_f32 v[92:93], v[92:93], v[226:227]
	v_pk_add_f32 v[90:91], v[90:91], v[222:223]
	v_pk_add_f32 v[82:83], v[82:83], v[206:207]
